# prompt attention: the step-closing barrier of each half-step moved ahead of the VALU-only softmax (fma+exp) block, so that block runs in the free-running interval instead of between two barriers
# speedup vs baseline: 1.0054x; 1.0054x over previous
; __device__ __forceinline__ void partialSM(f32x16& p0, f32x16& p1, float& m_reg, float& mn, float& alpha) {
;     ...
;     const float mnL = -mn * C2;
;     for (int r = 0; r < 16; ++r) p0[r] = fmaf(p0[r], C2, mnL); for (int r = 0; r < 16; ++r) p1[r] = fmaf(p1[r], C2, mnL);
;     for (int r = 0; r < 16; ++r) p0[r] = __builtin_amdgcn_exp2f(p0[r]);
; }
; __device__ __forceinline__ void finishSM(f32x16& p0, f32x16& p1, float alpha, float& l_reg, bf16x8& pa0, bf16x8& pa1, bf16x8& pa2, bf16x8& pa3) {
;     for (int r = 0; r < 16; ++r) p1[r] = __builtin_amdgcn_exp2f(p1[r]);
;     float ps = 0; for (int r = 0; r < 16; ++r) ps += p0[r]; for (int r = 0; r < 16; ++r) ps += p1[r];
;     { auto rr = __builtin_amdgcn_permlane32_swap(__float_as_uint(ps), __float_as_uint(ps), false, false);
;       ps = __uint_as_float(rr[0]) + __uint_as_float(rr[1]); }
;     l_reg = l_reg * alpha + ps;
; template <class TIn, class TOut>
; __device__ __forceinline__ void causal_swa_block(const BlockRef<TIn, TOut>& cur, const BlockRef<TIn, TOut>& nxt, int skv, int W, char* lds, Seam<TIn>& S) {
;     ...
;     for (int t = 1; t + 1 < NT; t += 2) {
;         HALF_STEP(pB0, pB1, mnB, alB, pA0, pA1, alA, t, 1, 0, 0);
;         HALF_STEP(pA0, pA1, mnA, alA, pB0, pB1, alB, t + 1, 0, 1, 1);
;     }
.LBB0_1246:
	s_waitcnt lgkmcnt(0)
	s_barrier
	v_cndmask_b32_e64 v180, v2, v247, s[4:5]
	v_mul_f32_e32 v2, 0xbe0293ee, v180
	s_waitcnt vmcnt(1)
	v_fmamk_f32 v13, v138, 0x3e0293ee, v2
	v_fmamk_f32 v138, v139, 0x3e0293ee, v2
	v_fmamk_f32 v139, v140, 0x3e0293ee, v2
	v_fmamk_f32 v140, v141, 0x3e0293ee, v2
	v_fmamk_f32 v141, v142, 0x3e0293ee, v2
	v_mov_b32_e32 v142, v2
	v_fmamk_f32 v3, v128, 0x3e0293ee, v2
	v_fmamk_f32 v4, v129, 0x3e0293ee, v2
	v_fmamk_f32 v5, v130, 0x3e0293ee, v2
	v_fmamk_f32 v6, v131, 0x3e0293ee, v2
	v_fmamk_f32 v7, v132, 0x3e0293ee, v2
	v_fmamk_f32 v8, v133, 0x3e0293ee, v2
	v_fmamk_f32 v9, v134, 0x3e0293ee, v2
	v_fmamk_f32 v10, v135, 0x3e0293ee, v2
	v_fmamk_f32 v11, v136, 0x3e0293ee, v2
	v_fmamk_f32 v12, v137, 0x3e0293ee, v2
	v_fmac_f32_e32 v142, 0x3e0293ee, v143
	v_exp_f32_e32 v191, v3
	v_exp_f32_e32 v193, v4
	v_exp_f32_e32 v189, v5
	v_exp_f32_e32 v192, v6
	v_exp_f32_e32 v188, v7
	v_exp_f32_e32 v190, v8
	v_exp_f32_e32 v186, v9
	v_exp_f32_e32 v187, v10
	v_exp_f32_e32 v182, v11
	v_exp_f32_e32 v185, v12
	s_waitcnt vmcnt(0)
	v_exp_f32_e32 v179, v13
	v_exp_f32_e32 v183, v138
	v_exp_f32_e32 v177, v139
	v_exp_f32_e32 v184, v140
	v_exp_f32_e32 v178, v141
	v_exp_f32_e32 v181, v142
	v_pk_fma_f32 v[128:129], v[126:127], s[44:45], v[2:3] op_sel_hi:[1,0,0]
	v_pk_fma_f32 v[130:131], v[124:125], s[44:45], v[2:3] op_sel_hi:[1,0,0]
	v_pk_fma_f32 v[132:133], v[122:123], s[44:45], v[2:3] op_sel_hi:[1,0,0]
	v_pk_fma_f32 v[134:135], v[120:121], s[44:45], v[2:3] op_sel_hi:[1,0,0]
	v_pk_fma_f32 v[136:137], v[118:119], s[44:45], v[2:3] op_sel_hi:[1,0,0]
	v_pk_fma_f32 v[138:139], v[116:117], s[44:45], v[2:3] op_sel_hi:[1,0,0]
	v_pk_fma_f32 v[140:141], v[114:115], s[44:45], v[2:3] op_sel_hi:[1,0,0]
	v_pk_fma_f32 v[142:143], v[112:113], s[44:45], v[2:3] op_sel_hi:[1,0,0]
	v_add_f32_e32 v2, v244, v245
	v_fmac_f32_e32 v2, v240, v241
	v_add_f32_e32 v241, v249, v250
	s_addk_i32 s68, 0x80
	s_add_i32 s61, s61, 2
	v_fmac_f32_e32 v241, v2, v15
	v_add_u32_e32 v243, 0xffffff80, v243
	s_cmp_ge_i32 s61, s59
	v_add_u32_e32 v14, 0x40000, v14
	v_mov_b32_e32 v240, v0
	s_cbranch_scc1 .LBB0_1263

; __device__ __forceinline__ void partialSM(f32x16& p0, f32x16& p1, float& m_reg, float& mn, float& alpha) {
;     ...
;     const float mnL = -mn * C2;
;     for (int r = 0; r < 16; ++r) p0[r] = fmaf(p0[r], C2, mnL); for (int r = 0; r < 16; ++r) p1[r] = fmaf(p1[r], C2, mnL);
;     for (int r = 0; r < 16; ++r) p0[r] = __builtin_amdgcn_exp2f(p0[r]);
.LBB0_1253:
	s_waitcnt lgkmcnt(0)
	s_barrier
	v_cndmask_b32_e64 v247, v0, v180, s[4:5]
	v_mul_f32_e32 v0, 0xbe0293ee, v247
	v_fmamk_f32 v80, v100, 0x3e0293ee, v0
	v_fmamk_f32 v81, v101, 0x3e0293ee, v0
	v_fmamk_f32 v82, v102, 0x3e0293ee, v0
	v_fmamk_f32 v83, v103, 0x3e0293ee, v0
	v_fmamk_f32 v116, v104, 0x3e0293ee, v0
	v_fmamk_f32 v117, v105, 0x3e0293ee, v0
	v_fmamk_f32 v118, v106, 0x3e0293ee, v0
	v_fmamk_f32 v119, v107, 0x3e0293ee, v0
	v_fmamk_f32 v120, v108, 0x3e0293ee, v0
	v_fmamk_f32 v121, v109, 0x3e0293ee, v0
	v_fmamk_f32 v122, v110, 0x3e0293ee, v0
	v_fmamk_f32 v123, v111, 0x3e0293ee, v0
	v_fmamk_f32 v112, v112, 0x3e0293ee, v0
	v_fmamk_f32 v113, v113, 0x3e0293ee, v0
	v_fmamk_f32 v114, v114, 0x3e0293ee, v0
	v_fmamk_f32 v115, v115, 0x3e0293ee, v0
	v_fmamk_f32 v100, v84, 0x3e0293ee, v0
	v_fmamk_f32 v109, v85, 0x3e0293ee, v0
	v_fmamk_f32 v110, v86, 0x3e0293ee, v0
	v_fmamk_f32 v111, v87, 0x3e0293ee, v0
	v_fmamk_f32 v180, v88, 0x3e0293ee, v0
	v_fmamk_f32 v101, v89, 0x3e0293ee, v0
	v_fmamk_f32 v102, v90, 0x3e0293ee, v0
	v_fmamk_f32 v103, v91, 0x3e0293ee, v0
	v_fmamk_f32 v104, v92, 0x3e0293ee, v0
	v_fmamk_f32 v105, v93, 0x3e0293ee, v0
	v_fmamk_f32 v106, v94, 0x3e0293ee, v0
	v_fmamk_f32 v107, v95, 0x3e0293ee, v0
	v_exp_f32_e32 v80, v80
	v_exp_f32_e32 v81, v81
	v_exp_f32_e32 v82, v82
	v_exp_f32_e32 v83, v83
	v_exp_f32_e32 v84, v116
	v_exp_f32_e32 v85, v117
	v_exp_f32_e32 v86, v118
	v_exp_f32_e32 v87, v119
	v_exp_f32_e32 v88, v120
	v_exp_f32_e32 v89, v121
	v_exp_f32_e32 v90, v122
	v_exp_f32_e32 v91, v123
	v_exp_f32_e32 v92, v112
	v_exp_f32_e32 v93, v113
	v_exp_f32_e32 v94, v114
	v_exp_f32_e32 v95, v115
	v_fmamk_f32 v108, v96, 0x3e0293ee, v0
	v_fmamk_f32 v181, v97, 0x3e0293ee, v0
	v_fmamk_f32 v182, v98, 0x3e0293ee, v0
	v_fmac_f32_e32 v0, 0x3e0293ee, v99
	s_add_i32 s4, s61, 1
	s_cmp_lt_i32 s4, s59
	s_cselect_b64 s[28:29], -1, 0
	s_cmp_ge_i32 s4, s59
	s_cbranch_scc1 .Lattn_h2_noload
	v_add_u32_e32 v200, 0x41, v248
	v_lshl_add_u64 v[2:3], v[200:201], 2, s[66:67]
	v_add_u32_e32 v200, 0x20000, v14
	v_lshlrev_b64 v[10:11], 1, v[200:201]
	v_add_u32_e32 v200, 0x30000, v14
	v_lshlrev_b64 v[12:13], 1, v[200:201]
	global_load_dword v246, v[2:3], off
	v_lshl_add_u64 v[2:3], s[64:65], 0, v[10:11]
	v_lshl_add_u64 v[6:7], s[64:65], 0, v[12:13]
	v_lshl_add_u64 v[10:11], s[62:63], 0, v[10:11]
	v_lshl_add_u64 v[176:177], s[62:63], 0, v[12:13]
	global_load_dwordx4 v[2:5], v[2:3], off
	s_nop 0
	global_load_dwordx4 v[6:9], v[6:7], off
	s_nop 0
	global_load_dwordx4 v[10:13], v[10:11], off
	s_nop 0
	global_load_dwordx4 v[176:179], v[176:177], off
